# P1 rotary tiles: cos/sin of all 8 row groups preloaded in first group (on top of rs preload + P5 epilogue preload)
# baseline (speedup 1.0000x reference)
;     __device__ __forceinline__ void operator()(const f32x4 (&acc)[2][2][4][2], const Unit& u, int wr, int wc, int fr, int fq) const {
;     ...
;                 const int row = row0 + ai * HALF + m * 16; const float rsv = rs[row] * sc;
;                 f32x4 cs = (f32x4){1.f, 1.f, 1.f, 1.f}, sn = (f32x4){0.f, 0.f, 0.f, 0.f};
;                 if (ropel) { const int t = row & 8191; cs = *(const f32x4*)(rope + t * 8 + 4 * fq); sn = *(const f32x4*)(rope + 65536 + t * 8 + 4 * fq); }
.LBB0_247:
	v_lshl_add_u32 v158, s2, 8, v168
	v_ashrrev_i32_e32 v159, 31, v158
	v_lshl_add_u64 v[160:161], v[158:159], 2, s[6:7]
	global_load_dword v162, v[160:161], off
	global_load_dword v231, v[160:161], off offset:64
	global_load_dword v232, v[160:161], off offset:128
	global_load_dword v233, v[160:161], off offset:192
	global_load_dword v234, v[160:161], off offset:512
	global_load_dword v235, v[160:161], off offset:576
	global_load_dword v236, v[160:161], off offset:640
	global_load_dword v237, v[160:161], off offset:704
	s_and_b64 s[88:89], s[78:79], s[94:95]
	v_mov_b32_e32 v132, 0
	v_mov_b32_e32 v128, 1.0
	v_mov_b32_e32 v129, 1.0
	v_mov_b32_e32 v130, 1.0
	v_mov_b32_e32 v131, 1.0
	v_mov_b32_e32 v133, 0
	v_mov_b32_e32 v134, 0
	v_mov_b32_e32 v135, 0
	s_and_saveexec_b64 s[2:3], s[88:89]
	s_cbranch_execz .LBB0_249
	v_lshlrev_b32_e32 v128, 5, v158
	v_and_b32_e32 v144, 0x3f9e0, v128
	v_lshl_add_u64 v[132:133], v[148:149], 0, v[144:145]
	v_lshl_add_u64 v[128:129], v[146:147], 0, v[144:145]
	global_load_dwordx4 v[182:185], v[128:129], off offset:512
	global_load_dwordx4 v[186:189], v[132:133], off offset:512
	global_load_dwordx4 v[190:193], v[128:129], off offset:1024
	global_load_dwordx4 v[194:197], v[132:133], off offset:1024
	global_load_dwordx4 v[198:201], v[128:129], off offset:1536
	global_load_dwordx4 v[202:205], v[132:133], off offset:1536
	s_mov_b64 s[98:99], 0x1000
	v_lshl_add_u64 v[246:247], v[128:129], 0, s[98:99]
	v_lshl_add_u64 v[248:249], v[132:133], 0, s[98:99]
	global_load_dwordx4 v[206:209], v[246:247], off
	global_load_dwordx4 v[210:213], v[248:249], off
	global_load_dwordx4 v[214:217], v[246:247], off offset:512
	global_load_dwordx4 v[218:221], v[248:249], off offset:512
	global_load_dwordx4 v[222:225], v[246:247], off offset:1024
	global_load_dwordx4 v[226:229], v[248:249], off offset:1024
	global_load_dwordx4 v[238:241], v[246:247], off offset:1536
	global_load_dwordx4 v[242:245], v[248:249], off offset:1536
	global_load_dwordx4 v[128:131], v[128:129], off
	s_nop 0
	global_load_dwordx4 v[132:135], v[132:133], off

;     __device__ __forceinline__ void operator()(const f32x4 (&acc)[2][2][4][2], const Unit& u, int wr, int wc, int fr, int fq) const {
;     ...
;                 if (ropel) { const int t = row & 8191; cs = *(const f32x4*)(rope + t * 8 + 4 * fq); sn = *(const f32x4*)(rope + 65536 + t * 8 + 4 * fq); }
.LBB0_257:
	v_or_b32_e32 v120, 16, v158
	v_ashrrev_i32_e32 v121, 31, v120
	v_cvt_pk_bf16_f32 v116, v116, v117
	v_cvt_pk_bf16_f32 v117, v118, v119
	v_cvt_pk_bf16_f32 v118, v112, v113
	v_cvt_pk_bf16_f32 v119, v114, v115
	global_store_dwordx4 v[166:167], v[116:119], off offset:256
	v_lshl_add_u64 v[112:113], v[120:121], 2, s[6:7]
	v_mov_b32_e32 v122, v231
	v_mov_b32_e32 v116, 0
	v_mov_b32_e32 v112, 1.0
	v_mov_b32_e32 v113, 1.0
	v_mov_b32_e32 v114, 1.0
	v_mov_b32_e32 v115, 1.0
	v_mov_b32_e32 v117, 0
	v_mov_b32_e32 v118, 0
	v_mov_b32_e32 v119, 0
	s_and_saveexec_b64 s[90:91], s[88:89]
	s_cbranch_execz .LBB0_259
	v_lshlrev_b32_e32 v112, 5, v120
	v_and_b32_e32 v144, 0x3fbe0, v112
	v_lshl_add_u64 v[116:117], v[148:149], 0, v[144:145]
	v_lshl_add_u64 v[112:113], v[146:147], 0, v[144:145]
	v_mov_b32_e32 v112, v182
	v_mov_b32_e32 v113, v183
	v_mov_b32_e32 v114, v184
	v_mov_b32_e32 v115, v185
	v_mov_b32_e32 v116, v186
	v_mov_b32_e32 v117, v187
	v_mov_b32_e32 v118, v188
	v_mov_b32_e32 v119, v189

;     __device__ __forceinline__ void operator()(const f32x4 (&acc)[2][2][4][2], const Unit& u, int wr, int wc, int fr, int fq) const {
;     ...
;                 if (ropel) { const int t = row & 8191; cs = *(const f32x4*)(rope + t * 8 + 4 * fq); sn = *(const f32x4*)(rope + 65536 + t * 8 + 4 * fq); }
.LBB0_267:
	v_or_b32_e32 v104, 32, v158
	v_ashrrev_i32_e32 v105, 31, v104
	v_cvt_pk_bf16_f32 v100, v100, v101
	v_cvt_pk_bf16_f32 v101, v102, v103
	v_cvt_pk_bf16_f32 v102, v96, v97
	v_cvt_pk_bf16_f32 v103, v98, v99
	global_store_dwordx4 v[120:121], v[100:103], off offset:256
	v_lshl_add_u64 v[96:97], v[104:105], 2, s[6:7]
	v_mov_b32_e32 v106, v232
	v_mov_b32_e32 v100, 0
	v_mov_b32_e32 v96, 1.0
	v_mov_b32_e32 v97, 1.0
	v_mov_b32_e32 v98, 1.0
	v_mov_b32_e32 v99, 1.0
	v_mov_b32_e32 v101, 0
	v_mov_b32_e32 v102, 0
	v_mov_b32_e32 v103, 0
	s_and_saveexec_b64 s[90:91], s[88:89]
	s_cbranch_execz .LBB0_269
	v_lshlrev_b32_e32 v96, 5, v104
	v_and_b32_e32 v144, 0x3fde0, v96
	v_lshl_add_u64 v[100:101], v[148:149], 0, v[144:145]
	v_lshl_add_u64 v[96:97], v[146:147], 0, v[144:145]
	v_mov_b32_e32 v96, v190
	v_mov_b32_e32 v97, v191
	v_mov_b32_e32 v98, v192
	v_mov_b32_e32 v99, v193
	v_mov_b32_e32 v100, v194
	v_mov_b32_e32 v101, v195
	v_mov_b32_e32 v102, v196
	v_mov_b32_e32 v103, v197

;     __device__ __forceinline__ void operator()(const f32x4 (&acc)[2][2][4][2], const Unit& u, int wr, int wc, int fr, int fq) const {
;     ...
;                 if (ropel) { const int t = row & 8191; cs = *(const f32x4*)(rope + t * 8 + 4 * fq); sn = *(const f32x4*)(rope + 65536 + t * 8 + 4 * fq); }
.LBB0_277:
	v_or_b32_e32 v88, 48, v158
	v_ashrrev_i32_e32 v89, 31, v88
	v_cvt_pk_bf16_f32 v84, v84, v85
	v_cvt_pk_bf16_f32 v85, v86, v87
	v_cvt_pk_bf16_f32 v86, v80, v81
	v_cvt_pk_bf16_f32 v87, v82, v83
	global_store_dwordx4 v[104:105], v[84:87], off offset:256
	v_lshl_add_u64 v[80:81], v[88:89], 2, s[6:7]
	v_mov_b32_e32 v90, v233
	v_mov_b32_e32 v84, 0
	v_mov_b32_e32 v80, 1.0
	v_mov_b32_e32 v81, 1.0
	v_mov_b32_e32 v82, 1.0
	v_mov_b32_e32 v83, 1.0
	v_mov_b32_e32 v85, 0
	v_mov_b32_e32 v86, 0
	v_mov_b32_e32 v87, 0
	s_and_saveexec_b64 s[90:91], s[88:89]
	s_cbranch_execz .LBB0_279
	v_lshlrev_b32_e32 v80, 5, v88
	v_and_b32_e32 v144, 0x3ffe0, v80
	v_lshl_add_u64 v[84:85], v[148:149], 0, v[144:145]
	v_lshl_add_u64 v[80:81], v[146:147], 0, v[144:145]
	v_mov_b32_e32 v80, v198
	v_mov_b32_e32 v81, v199
	v_mov_b32_e32 v82, v200
	v_mov_b32_e32 v83, v201
	v_mov_b32_e32 v84, v202
	v_mov_b32_e32 v85, v203
	v_mov_b32_e32 v86, v204
	v_mov_b32_e32 v87, v205

;     __device__ __forceinline__ void operator()(const f32x4 (&acc)[2][2][4][2], const Unit& u, int wr, int wc, int fr, int fq) const {
;     ...
;                 if (ropel) { const int t = row & 8191; cs = *(const f32x4*)(rope + t * 8 + 4 * fq); sn = *(const f32x4*)(rope + 65536 + t * 8 + 4 * fq); }
.LBB0_287:
	v_cvt_pk_bf16_f32 v68, v68, v69
	v_cvt_pk_bf16_f32 v69, v70, v71
	v_cvt_pk_bf16_f32 v70, v64, v65
	s_nop 0
	v_cvt_pk_bf16_f32 v71, v66, v67
	global_store_dwordx4 v[88:89], v[68:71], off offset:256
	v_mov_b32_e32 v72, v234
	v_add_u32_e32 v74, 0x80, v158
	v_ashrrev_i32_e32 v75, 31, v74
	v_mov_b32_e32 v68, 0
	v_mov_b32_e32 v64, 1.0
	v_mov_b32_e32 v65, 1.0
	v_mov_b32_e32 v66, 1.0
	v_mov_b32_e32 v67, 1.0
	v_mov_b32_e32 v69, 0
	v_mov_b32_e32 v70, 0
	v_mov_b32_e32 v71, 0
	s_and_saveexec_b64 s[90:91], s[88:89]
	s_cbranch_execz .LBB0_289
	v_lshlrev_b32_e32 v64, 5, v74
	v_and_b32_e32 v144, 0x3f9e0, v64
	v_lshl_add_u64 v[68:69], v[148:149], 0, v[144:145]
	v_lshl_add_u64 v[64:65], v[146:147], 0, v[144:145]
	v_mov_b32_e32 v64, v206
	v_mov_b32_e32 v65, v207
	v_mov_b32_e32 v66, v208
	v_mov_b32_e32 v67, v209
	v_mov_b32_e32 v68, v210
	v_mov_b32_e32 v69, v211
	v_mov_b32_e32 v70, v212
	v_mov_b32_e32 v71, v213

;     __device__ __forceinline__ void operator()(const f32x4 (&acc)[2][2][4][2], const Unit& u, int wr, int wc, int fr, int fq) const {
;     ...
;                 if (ropel) { const int t = row & 8191; cs = *(const f32x4*)(rope + t * 8 + 4 * fq); sn = *(const f32x4*)(rope + 65536 + t * 8 + 4 * fq); }
.LBB0_297:
	v_cvt_pk_bf16_f32 v52, v52, v53
	v_cvt_pk_bf16_f32 v53, v54, v55
	v_cvt_pk_bf16_f32 v54, v48, v49
	s_nop 0
	v_cvt_pk_bf16_f32 v55, v50, v51
	global_store_dwordx4 v[74:75], v[52:55], off offset:256
	v_mov_b32_e32 v56, v235
	v_add_u32_e32 v58, 0x90, v158
	v_ashrrev_i32_e32 v59, 31, v58
	v_mov_b32_e32 v52, 0
	v_mov_b32_e32 v48, 1.0
	v_mov_b32_e32 v49, 1.0
	v_mov_b32_e32 v50, 1.0
	v_mov_b32_e32 v51, 1.0
	v_mov_b32_e32 v53, 0
	v_mov_b32_e32 v54, 0
	v_mov_b32_e32 v55, 0
	s_and_saveexec_b64 s[90:91], s[88:89]
	s_cbranch_execz .LBB0_299
	v_lshlrev_b32_e32 v48, 5, v58
	v_and_b32_e32 v144, 0x3fbe0, v48
	v_lshl_add_u64 v[52:53], v[148:149], 0, v[144:145]
	v_lshl_add_u64 v[48:49], v[146:147], 0, v[144:145]
	v_mov_b32_e32 v48, v214
	v_mov_b32_e32 v49, v215
	v_mov_b32_e32 v50, v216
	v_mov_b32_e32 v51, v217
	v_mov_b32_e32 v52, v218
	v_mov_b32_e32 v53, v219
	v_mov_b32_e32 v54, v220
	v_mov_b32_e32 v55, v221

;     __device__ __forceinline__ void operator()(const f32x4 (&acc)[2][2][4][2], const Unit& u, int wr, int wc, int fr, int fq) const {
;     ...
;                 if (ropel) { const int t = row & 8191; cs = *(const f32x4*)(rope + t * 8 + 4 * fq); sn = *(const f32x4*)(rope + 65536 + t * 8 + 4 * fq); }
.LBB0_307:
	v_cvt_pk_bf16_f32 v36, v36, v37
	v_cvt_pk_bf16_f32 v37, v38, v39
	v_cvt_pk_bf16_f32 v38, v32, v33
	s_nop 0
	v_cvt_pk_bf16_f32 v39, v34, v35
	global_store_dwordx4 v[58:59], v[36:39], off offset:256
	v_mov_b32_e32 v40, v236
	v_add_u32_e32 v42, 0xa0, v158
	v_ashrrev_i32_e32 v43, 31, v42
	v_mov_b32_e32 v36, 0
	v_mov_b32_e32 v32, 1.0
	v_mov_b32_e32 v33, 1.0
	v_mov_b32_e32 v34, 1.0
	v_mov_b32_e32 v35, 1.0
	v_mov_b32_e32 v37, 0
	v_mov_b32_e32 v38, 0
	v_mov_b32_e32 v39, 0
	s_and_saveexec_b64 s[90:91], s[88:89]
	s_cbranch_execz .LBB0_309
	v_lshlrev_b32_e32 v32, 5, v42
	v_and_b32_e32 v144, 0x3fde0, v32
	v_lshl_add_u64 v[36:37], v[148:149], 0, v[144:145]
	v_lshl_add_u64 v[32:33], v[146:147], 0, v[144:145]
	v_mov_b32_e32 v32, v222
	v_mov_b32_e32 v33, v223
	v_mov_b32_e32 v34, v224
	v_mov_b32_e32 v35, v225
	v_mov_b32_e32 v36, v226
	v_mov_b32_e32 v37, v227
	v_mov_b32_e32 v38, v228
	v_mov_b32_e32 v39, v229

;     __device__ __forceinline__ void operator()(const f32x4 (&acc)[2][2][4][2], const Unit& u, int wr, int wc, int fr, int fq) const {
;     ...
;                 if (ropel) { const int t = row & 8191; cs = *(const f32x4*)(rope + t * 8 + 4 * fq); sn = *(const f32x4*)(rope + 65536 + t * 8 + 4 * fq); }
.LBB0_317:
	v_cvt_pk_bf16_f32 v20, v20, v21
	v_cvt_pk_bf16_f32 v21, v22, v23
	v_cvt_pk_bf16_f32 v22, v16, v17
	s_nop 0
	v_cvt_pk_bf16_f32 v23, v18, v19
	global_store_dwordx4 v[42:43], v[20:23], off offset:256
	v_mov_b32_e32 v24, v237
	v_add_u32_e32 v26, 0xb0, v158
	v_ashrrev_i32_e32 v27, 31, v26
	v_mov_b32_e32 v20, 0
	v_mov_b32_e32 v16, 1.0
	v_mov_b32_e32 v17, 1.0
	v_mov_b32_e32 v18, 1.0
	v_mov_b32_e32 v19, 1.0
	v_mov_b32_e32 v21, 0
	v_mov_b32_e32 v22, 0
	v_mov_b32_e32 v23, 0
	s_and_saveexec_b64 s[90:91], s[88:89]
	s_cbranch_execz .LBB0_319
	v_lshlrev_b32_e32 v16, 5, v26
	v_and_b32_e32 v144, 0x3ffe0, v16
	v_lshl_add_u64 v[20:21], v[148:149], 0, v[144:145]
	v_lshl_add_u64 v[16:17], v[146:147], 0, v[144:145]
	v_mov_b32_e32 v16, v238
	v_mov_b32_e32 v17, v239
	v_mov_b32_e32 v18, v240
	v_mov_b32_e32 v19, v241
	v_mov_b32_e32 v20, v242
	v_mov_b32_e32 v21, v243
	v_mov_b32_e32 v22, v244
	v_mov_b32_e32 v23, v245
